# speedup vs baseline: 1.0051x; 1.0001x over previous
; __device__ __forceinline__ float frcp(float x) { return __builtin_amdgcn_rcpf(x); }
; __device__ __forceinline__ float tanhf_(float x) { return 1.0f - 2.0f * frcp(__expf(2.0f * x) + 1.0f); }
.LBB0_1328:
	v_cndmask_b32_e64 v0, 0, 1, s[8:9]
	v_cmp_ne_u32_e64 s[6:7], 1, v0
	s_andn2_b64 vcc, exec, s[8:9]
	s_cbranch_vccnz .LBB0_1330
	v_add3_u32 v0, v128, s40, 16
	v_add3_u32 v102, v147, s41, -16
	v_cndmask_b32_e64 v0, v102, v0, s[0:1]
	v_cmp_gt_u32_e32 vcc, s18, v0
	v_lshlrev_b32_e32 v103, 16, v70
	v_lshlrev_b32_e32 v102, 16, v66
	v_cndmask_b32_e64 v151, 0, 1.0, vcc
	v_cmp_eq_u32_e32 vcc, 0, v0
	v_lshlrev_b32_e32 v104, 16, v74
	v_and_b32_e32 v105, 0xffff0000, v74
	v_cndmask_b32_e64 v150, 1.0, 0, vcc
	v_pk_mul_f32 v[102:103], v[150:151], v[102:103]
	v_lshlrev_b32_e32 v152, 16, v75
	v_add_f32_e32 v0, v102, v103
	v_and_b32_e32 v103, 0xffff0000, v70
	v_and_b32_e32 v102, 0xffff0000, v66
	v_fma_f32 v0, v0, 0.5, -v104
	v_pk_mul_f32 v[102:103], v[150:151], v[102:103]
	v_fmac_f32_e32 v104, v50, v0
	v_add_f32_e32 v0, v102, v103
	v_lshlrev_b32_e32 v103, 16, v71
	v_lshlrev_b32_e32 v102, 16, v67
	v_fma_f32 v0, v0, 0.5, -v105
	v_pk_mul_f32 v[102:103], v[150:151], v[102:103]
	v_fmac_f32_e32 v105, v51, v0
	v_add_f32_e32 v0, v102, v103
	v_and_b32_e32 v103, 0xffff0000, v71
	v_and_b32_e32 v102, 0xffff0000, v67
	v_fma_f32 v0, v0, 0.5, -v152
	v_pk_mul_f32 v[102:103], v[150:151], v[102:103]
	v_and_b32_e32 v153, 0xffff0000, v75
	v_fmac_f32_e32 v152, v52, v0
	v_add_f32_e32 v0, v102, v103
	v_lshlrev_b32_e32 v103, 16, v72
	v_lshlrev_b32_e32 v102, 16, v68
	v_fma_f32 v0, v0, 0.5, -v153
	v_pk_mul_f32 v[102:103], v[150:151], v[102:103]
	v_lshlrev_b32_e32 v154, 16, v76
	v_fmac_f32_e32 v153, v53, v0
	v_add_f32_e32 v0, v102, v103
	v_and_b32_e32 v103, 0xffff0000, v72
	v_and_b32_e32 v102, 0xffff0000, v68
	v_fma_f32 v0, v0, 0.5, -v154
	v_pk_mul_f32 v[102:103], v[150:151], v[102:103]
	v_and_b32_e32 v155, 0xffff0000, v76
	v_fmac_f32_e32 v154, v54, v0
	v_add_f32_e32 v0, v102, v103
	v_lshlrev_b32_e32 v103, 16, v73
	v_lshlrev_b32_e32 v102, 16, v69
	v_fma_f32 v0, v0, 0.5, -v155
	v_pk_mul_f32 v[102:103], v[150:151], v[102:103]
	v_lshlrev_b32_e32 v156, 16, v77
	v_fmac_f32_e32 v155, v55, v0
	v_add_f32_e32 v0, v102, v103
	v_and_b32_e32 v103, 0xffff0000, v73
	v_and_b32_e32 v102, 0xffff0000, v69
	v_fma_f32 v0, v0, 0.5, -v156
	v_pk_mul_f32 v[102:103], v[150:151], v[102:103]
	v_fmac_f32_e32 v156, v56, v0
	v_add_f32_e32 v0, v102, v103
	v_mul_f32_e32 v102, 0x4038aa3b, v104
	v_exp_f32_e32 v102, v102
	v_mul_f32_e32 v103, 0x4038aa3b, v105
	v_exp_f32_e32 v103, v103
	v_and_b32_e32 v157, 0xffff0000, v77
	v_fma_f32 v0, v0, 0.5, -v157
	v_fmac_f32_e32 v157, v57, v0
	v_add_f32_e32 v0, 1.0, v102
	v_rcp_f32_e32 v102, v0
	v_add_f32_e32 v0, 1.0, v103
	v_mul_f32_e32 v103, 0x4038aa3b, v152
	v_exp_f32_e32 v104, v103
	v_mul_f32_e32 v103, 0x4038aa3b, v153
	v_exp_f32_e32 v105, v103
	v_rcp_f32_e32 v103, v0
	v_add_f32_e32 v0, 1.0, v104
	v_rcp_f32_e32 v104, v0
	v_add_f32_e32 v0, 1.0, v105
	v_mul_f32_e32 v105, 0x4038aa3b, v154
	v_exp_f32_e32 v152, v105
	v_mul_f32_e32 v105, 0x4038aa3b, v155
	v_exp_f32_e32 v153, v105
	v_rcp_f32_e32 v105, v0
	v_add_f32_e32 v0, 1.0, v152
	v_rcp_f32_e32 v152, v0
	v_add_f32_e32 v0, 1.0, v153
	v_mul_f32_e32 v153, 0x4038aa3b, v156
	v_exp_f32_e32 v154, v153
	v_mul_f32_e32 v153, 0x4038aa3b, v157
	v_exp_f32_e32 v155, v153
	v_rcp_f32_e32 v153, v0
	v_pk_fma_f32 v[102:103], v[102:103], 2.0, 1.0 op_sel_hi:[1,0,0] neg_lo:[1,0,0] neg_hi:[1,0,0]
	v_pk_fma_f32 v[104:105], v[104:105], 2.0, 1.0 op_sel_hi:[1,0,0] neg_lo:[1,0,0] neg_hi:[1,0,0]
	v_add_f32_e32 v0, 1.0, v154
	v_pk_fma_f32 v[152:153], v[152:153], 2.0, 1.0 op_sel_hi:[1,0,0] neg_lo:[1,0,0] neg_hi:[1,0,0]
	v_cvt_pk_bf16_f32 v102, v102, v103
	v_cvt_pk_bf16_f32 v103, v104, v105
	v_cvt_pk_bf16_f32 v104, v152, v153
	v_lshlrev_b32_e32 v153, 16, v86
	v_lshlrev_b32_e32 v152, 16, v82
	v_rcp_f32_e32 v154, v0
	v_add_f32_e32 v0, 1.0, v155
	v_pk_mul_f32 v[152:153], v[150:151], v[152:153]
	v_lshlrev_b32_e32 v158, 16, v78
	v_rcp_f32_e32 v155, v0
	v_add_f32_e32 v0, v152, v153
	v_and_b32_e32 v153, 0xffff0000, v86
	v_and_b32_e32 v152, 0xffff0000, v82
	v_fma_f32 v0, v0, 0.5, -v158
	v_pk_mul_f32 v[152:153], v[150:151], v[152:153]
	v_and_b32_e32 v159, 0xffff0000, v78
	v_fmac_f32_e32 v158, v58, v0
	v_add_f32_e32 v0, v152, v153
	v_lshlrev_b32_e32 v153, 16, v87
	v_lshlrev_b32_e32 v152, 16, v83
	v_fma_f32 v0, v0, 0.5, -v159
	v_pk_mul_f32 v[152:153], v[150:151], v[152:153]
	v_lshlrev_b32_e32 v160, 16, v79
	v_fmac_f32_e32 v159, v59, v0
	v_add_f32_e32 v0, v152, v153
	v_and_b32_e32 v153, 0xffff0000, v87
	v_and_b32_e32 v152, 0xffff0000, v83
	v_fma_f32 v0, v0, 0.5, -v160
	v_pk_mul_f32 v[152:153], v[150:151], v[152:153]
	v_and_b32_e32 v161, 0xffff0000, v79
	v_fmac_f32_e32 v160, v60, v0
	v_add_f32_e32 v0, v152, v153
	v_lshlrev_b32_e32 v153, 16, v88
	v_lshlrev_b32_e32 v152, 16, v84
	v_fma_f32 v0, v0, 0.5, -v161
	v_pk_mul_f32 v[152:153], v[150:151], v[152:153]
	v_lshlrev_b32_e32 v162, 16, v80
	v_fmac_f32_e32 v161, v61, v0
	v_add_f32_e32 v0, v152, v153
	v_and_b32_e32 v153, 0xffff0000, v88
	v_and_b32_e32 v152, 0xffff0000, v84
	v_fma_f32 v0, v0, 0.5, -v162
	v_pk_mul_f32 v[152:153], v[150:151], v[152:153]
	v_and_b32_e32 v163, 0xffff0000, v80
	v_fmac_f32_e32 v162, v62, v0
	v_add_f32_e32 v0, v152, v153
	v_lshlrev_b32_e32 v153, 16, v89
	v_lshlrev_b32_e32 v152, 16, v85
	v_fma_f32 v0, v0, 0.5, -v163
	v_pk_mul_f32 v[152:153], v[150:151], v[152:153]
	v_lshlrev_b32_e32 v164, 16, v81
	v_fmac_f32_e32 v163, v63, v0
	v_add_f32_e32 v0, v152, v153
	v_and_b32_e32 v153, 0xffff0000, v89
	v_and_b32_e32 v152, 0xffff0000, v85
	v_fma_f32 v0, v0, 0.5, -v164
	v_pk_mul_f32 v[150:151], v[150:151], v[152:153]
	v_fmac_f32_e32 v164, v64, v0
	v_add_f32_e32 v0, v150, v151
	v_mul_f32_e32 v150, 0x4038aa3b, v158
	v_exp_f32_e32 v150, v150
	v_mul_f32_e32 v151, 0x4038aa3b, v159
	v_exp_f32_e32 v151, v151
	v_and_b32_e32 v165, 0xffff0000, v81
	v_fma_f32 v0, v0, 0.5, -v165
	v_fmac_f32_e32 v165, v65, v0
	v_add_f32_e32 v0, 1.0, v150
	v_rcp_f32_e32 v150, v0
	v_add_f32_e32 v0, 1.0, v151
	v_mul_f32_e32 v151, 0x4038aa3b, v160
	v_exp_f32_e32 v152, v151
	v_mul_f32_e32 v151, 0x4038aa3b, v161
	v_exp_f32_e32 v153, v151
	v_rcp_f32_e32 v151, v0
	v_add_f32_e32 v0, 1.0, v152
	v_rcp_f32_e32 v152, v0
	v_add_f32_e32 v0, 1.0, v153
	v_pk_fma_f32 v[154:155], v[154:155], 2.0, 1.0 op_sel_hi:[1,0,0] neg_lo:[1,0,0] neg_hi:[1,0,0]
	v_mul_f32_e32 v153, 0x4038aa3b, v162
	v_cvt_pk_bf16_f32 v105, v154, v155
	v_exp_f32_e32 v154, v153
	v_mul_f32_e32 v153, 0x4038aa3b, v163
	v_exp_f32_e32 v155, v153
	v_rcp_f32_e32 v153, v0
	v_add_f32_e32 v0, 1.0, v154
	v_rcp_f32_e32 v154, v0
	v_add_f32_e32 v0, 1.0, v155
	v_mul_f32_e32 v155, 0x4038aa3b, v164
	v_exp_f32_e32 v156, v155
	v_mul_f32_e32 v155, 0x4038aa3b, v165
	v_exp_f32_e32 v157, v155
	v_rcp_f32_e32 v155, v0
	v_add_f32_e32 v0, 1.0, v156
	v_rcp_f32_e32 v156, v0
	v_add_f32_e32 v0, 1.0, v157
	v_rcp_f32_e32 v157, v0
	v_pk_fma_f32 v[150:151], v[150:151], 2.0, 1.0 op_sel_hi:[1,0,0] neg_lo:[1,0,0] neg_hi:[1,0,0]
	v_pk_fma_f32 v[152:153], v[152:153], 2.0, 1.0 op_sel_hi:[1,0,0] neg_lo:[1,0,0] neg_hi:[1,0,0]
	v_pk_fma_f32 v[154:155], v[154:155], 2.0, 1.0 op_sel_hi:[1,0,0] neg_lo:[1,0,0] neg_hi:[1,0,0]
	v_pk_fma_f32 v[158:159], v[156:157], 2.0, 1.0 op_sel_hi:[1,0,0] neg_lo:[1,0,0] neg_hi:[1,0,0]
	v_cvt_pk_bf16_f32 v150, v150, v151
	v_cvt_pk_bf16_f32 v151, v152, v153
	v_cvt_pk_bf16_f32 v152, v154, v155
	v_cvt_pk_bf16_f32 v153, v158, v159
	v_mfma_f32_16x16x32_bf16 v[154:157], v[102:105], v[18:21], 0
	s_add_i32 s8, s19, 1
	s_cmp_lg_u32 s19, 2
	v_mfma_f32_16x16x32_bf16 v[154:157], v[150:153], v[22:25], v[154:157]
	s_nop 7
	v_add_f32_e32 v0, v129, v154
	v_add_f32_e32 v154, v129, v155
	v_mul_f32_e32 v154, 0xbfb8aa3b, v154
	v_exp_f32_e32 v154, v154
	v_lshl_or_b32 v155, s19, 12, v143
	v_add_u32_e32 v158, v144, v155
	v_add_f32_e32 v155, v129, v156
	v_add_f32_e32 v154, 1.0, v154
	v_rcp_f32_e32 v154, v154
	v_mul_f32_e32 v155, 0xbfb8aa3b, v155
	v_exp_f32_e32 v155, v155
	v_mul_f32_e32 v0, 0xbfb8aa3b, v0
	v_mul_f32_e32 v154, 0xbf60028b, v154
	v_exp_f32_e32 v159, v154
	v_add_f32_e32 v154, 1.0, v155
	v_rcp_f32_e32 v154, v154
	v_add_f32_e32 v155, v129, v157
	v_mul_f32_e32 v155, 0xbfb8aa3b, v155
	v_exp_f32_e32 v160, v155
	v_mul_f32_e32 v161, 0xbf1b4598, v154
	v_mfma_f32_16x16x32_bf16 v[154:157], v[102:105], v[26:29], 0
	v_exp_f32_e32 v0, v0
	v_add_f32_e32 v160, 1.0, v160
	v_rcp_f32_e32 v160, v160
	v_mfma_f32_16x16x32_bf16 v[154:157], v[150:153], v[30:33], v[154:157]
	v_add_f32_e32 v0, 1.0, v0
	v_rcp_f32_e32 v0, v0
	v_mul_f32_e32 v161, 0x3fb8aa3b, v161
	v_exp_f32_e32 v161, v161
	s_nop 2
	v_add_f32_e32 v154, v130, v154
	v_mul_f32_e32 v154, 0xbfb8aa3b, v154
	v_add_f32_e32 v155, v130, v155
	v_exp_f32_e32 v154, v154
	v_mul_f32_e32 v155, 0xbfb8aa3b, v155
	v_exp_f32_e32 v155, v155
	v_add_f32_e32 v156, v130, v156
	v_add_f32_e32 v154, 1.0, v154
	v_rcp_f32_e32 v154, v154
	v_add_f32_e32 v155, 1.0, v155
	v_rcp_f32_e32 v155, v155
	v_mul_f32_e32 v156, 0xbfb8aa3b, v156
	v_exp_f32_e32 v156, v156
	v_mul_f32_e32 v0, 0xbf60028b, v0
	v_mul_f32_e32 v154, 0xbf60028b, v154
	v_exp_f32_e32 v0, v0
	v_exp_f32_e32 v154, v154
	v_mul_f32_e32 v155, 0xbf60028b, v155
	v_exp_f32_e32 v155, v155
	v_add_f32_e32 v156, 1.0, v156
	v_rcp_f32_e32 v156, v156
	ds_write2_b32 v158, v0, v154 offset1:16
	ds_write2_b32 v158, v159, v155 offset0:64 offset1:80
	v_add_f32_e32 v154, v130, v157
	v_mul_f32_e32 v154, 0xbfb8aa3b, v154
	v_mul_f32_e32 v0, 0xbf1b4598, v156
	v_exp_f32_e32 v159, v154
	v_mfma_f32_16x16x32_bf16 v[154:157], v[102:105], v[34:37], 0
	v_mul_f32_e32 v0, 0x3fb8aa3b, v0
	v_mul_f32_e32 v160, 0xbf60028b, v160
	v_add_f32_e32 v159, 1.0, v159
	v_mfma_f32_16x16x32_bf16 v[154:157], v[150:153], v[38:41], v[154:157]
	v_rcp_f32_e32 v159, v159
	v_exp_f32_e32 v0, v0
	v_exp_f32_e32 v160, v160
	v_mfma_f32_16x16x32_bf16 v[102:105], v[102:105], v[42:45], 0
	s_nop 2
	v_add_f32_e32 v154, v131, v154
	v_mul_f32_e32 v154, 0xbfb8aa3b, v154
	v_exp_f32_e32 v154, v154
	v_add_f32_e32 v155, v131, v155
	v_mfma_f32_16x16x32_bf16 v[102:105], v[150:153], v[46:49], v[102:105]
	v_mul_f32_e32 v155, 0xbfb8aa3b, v155
	v_add_f32_e32 v154, 1.0, v154
	v_mul_f32_e32 v159, 0xbf60028b, v159
	v_rcp_f32_e32 v154, v154
	v_exp_f32_e32 v155, v155
	v_exp_f32_e32 v159, v159
	s_nop 1
	v_add_f32_e32 v102, v132, v102
	v_mul_f32_e32 v102, 0xbfb8aa3b, v102
	v_add_f32_e32 v103, v132, v103
	ds_write2_b32 v158, v161, v0 offset0:128 offset1:144
	ds_write2_b32 v158, v160, v159 offset0:192 offset1:208
	v_mul_f32_e32 v0, 0xbf1b4598, v154
	v_add_f32_e32 v154, 1.0, v155
	v_add_f32_e32 v155, v131, v156
	v_exp_f32_e32 v102, v102
	v_mul_f32_e32 v103, 0xbfb8aa3b, v103
	v_add_f32_e32 v104, v132, v104
	v_mul_f32_e32 v155, 0xbfb8aa3b, v155
	v_add_f32_e32 v156, v131, v157
	v_exp_f32_e32 v103, v103
	v_mul_f32_e32 v104, 0xbfb8aa3b, v104
	v_add_f32_e32 v105, v132, v105
	v_exp_f32_e32 v155, v155
	v_mul_f32_e32 v156, 0xbfb8aa3b, v156
	v_exp_f32_e32 v104, v104
	v_mul_f32_e32 v105, 0xbfb8aa3b, v105
	v_exp_f32_e32 v156, v156
	v_exp_f32_e32 v105, v105
	v_add_f32_e32 v102, 1.0, v102
	v_rcp_f32_e32 v102, v102
	v_add_f32_e32 v103, 1.0, v103
	v_rcp_f32_e32 v154, v154
	v_add_f32_e32 v155, 1.0, v155
	v_rcp_f32_e32 v103, v103
	v_add_f32_e32 v104, 1.0, v104
	v_rcp_f32_e32 v155, v155
	v_add_f32_e32 v156, 1.0, v156
	v_rcp_f32_e32 v104, v104
	v_add_f32_e32 v105, 1.0, v105
	v_rcp_f32_e32 v156, v156
	v_rcp_f32_e32 v105, v105
	v_mul_f32_e32 v0, 0x3fb8aa3b, v0
	v_mul_f32_e32 v102, 0xbf60028b, v102
	v_exp_f32_e32 v0, v0
	v_mul_f32_e32 v154, 0xbf60028b, v154
	v_exp_f32_e32 v102, v102
	v_mul_f32_e32 v103, 0xbf60028b, v103
	v_exp_f32_e32 v154, v154
	v_mul_f32_e32 v155, 0xbf60028b, v155
	v_exp_f32_e32 v103, v103
	v_mul_f32_e32 v104, 0xbf60028b, v104
	v_exp_f32_e32 v155, v155
	v_mul_f32_e32 v156, 0xbf60028b, v156
	v_exp_f32_e32 v104, v104
	v_mul_f32_e32 v105, 0xbf60028b, v105
	v_exp_f32_e32 v150, v156
	v_exp_f32_e32 v105, v105
	s_cselect_b32 s19, s8, 0
	ds_write2_b32 v158, v0, v102 offset0:32 offset1:48
	ds_write2_b32 v158, v154, v103 offset0:96 offset1:112
	ds_write2_b32 v158, v155, v104 offset0:160 offset1:176
	ds_write2_b32 v158, v150, v105 offset0:224 offset1:240

.LBB0_1339:
	s_and_b64 vcc, exec, s[10:11]
	s_cbranch_vccnz .LBB0_1341
	v_cndmask_b32_e64 v0, v148, v11, s[0:1]
	v_cmp_gt_u32_e32 vcc, s18, v0
	v_and_b32_e32 v103, 0xffff0000, v127
	v_and_b32_e32 v102, 0xffff0000, v126
	v_cndmask_b32_e64 v161, 0, 1.0, vcc
	v_cmp_eq_u32_e32 vcc, 0, v0
	v_lshlrev_b32_e32 v127, 16, v127
	v_lshlrev_b32_e32 v126, 16, v126
	v_cndmask_b32_e64 v160, 1.0, 0, vcc
	v_pk_mul_f32 v[126:127], v[160:161], v[126:127]
	v_lshlrev_b32_e32 v11, 16, v94
	v_add_f32_e32 v0, v126, v127
	v_fma_f32 v0, v0, 0.5, -v11
	v_pk_mul_f32 v[102:103], v[160:161], v[102:103]
	v_and_b32_e32 v162, 0xffff0000, v94
	v_fmac_f32_e32 v11, v50, v0
	v_add_f32_e32 v0, v102, v103
	v_lshlrev_b32_e32 v103, 16, v125
	v_lshlrev_b32_e32 v102, 16, v124
	v_fma_f32 v0, v0, 0.5, -v162
	v_pk_mul_f32 v[102:103], v[160:161], v[102:103]
	v_lshlrev_b32_e32 v163, 16, v95
	v_and_b32_e32 v105, 0xffff0000, v125
	v_and_b32_e32 v104, 0xffff0000, v124
	v_fmac_f32_e32 v162, v51, v0
	v_add_f32_e32 v0, v102, v103
	v_fma_f32 v0, v0, 0.5, -v163
	v_pk_mul_f32 v[102:103], v[160:161], v[104:105]
	v_and_b32_e32 v164, 0xffff0000, v95
	v_fmac_f32_e32 v163, v52, v0
	v_add_f32_e32 v0, v102, v103
	v_lshlrev_b32_e32 v103, 16, v123
	v_lshlrev_b32_e32 v102, 16, v122
	v_fma_f32 v0, v0, 0.5, -v164
	v_pk_mul_f32 v[102:103], v[160:161], v[102:103]
	v_lshlrev_b32_e32 v165, 16, v96
	v_and_b32_e32 v149, 0xffff0000, v123
	v_and_b32_e32 v148, 0xffff0000, v122
	v_fmac_f32_e32 v164, v53, v0
	v_add_f32_e32 v0, v102, v103
	v_fma_f32 v0, v0, 0.5, -v165
	v_pk_mul_f32 v[102:103], v[160:161], v[148:149]
	v_and_b32_e32 v166, 0xffff0000, v96
	v_fmac_f32_e32 v165, v54, v0
	v_add_f32_e32 v0, v102, v103
	v_lshlrev_b32_e32 v103, 16, v121
	v_lshlrev_b32_e32 v102, 16, v120
	v_fma_f32 v0, v0, 0.5, -v166
	v_pk_mul_f32 v[102:103], v[160:161], v[102:103]
	v_lshlrev_b32_e32 v167, 16, v97
	v_and_b32_e32 v151, 0xffff0000, v121
	v_and_b32_e32 v150, 0xffff0000, v120
	v_fmac_f32_e32 v166, v55, v0
	v_add_f32_e32 v0, v102, v103
	v_fma_f32 v0, v0, 0.5, -v167
	v_pk_mul_f32 v[102:103], v[160:161], v[150:151]
	v_fmac_f32_e32 v167, v56, v0
	v_add_f32_e32 v0, v102, v103
	v_mul_f32_e32 v11, 0x4038aa3b, v11
	v_exp_f32_e32 v11, v11
	v_mul_f32_e32 v102, 0x4038aa3b, v162
	v_exp_f32_e32 v103, v102
	v_and_b32_e32 v168, 0xffff0000, v97
	v_fma_f32 v0, v0, 0.5, -v168
	v_fmac_f32_e32 v168, v57, v0
	v_add_f32_e32 v0, 1.0, v11
	v_rcp_f32_e32 v102, v0
	v_add_f32_e32 v0, 1.0, v103
	v_mul_f32_e32 v11, 0x4038aa3b, v163
	v_exp_f32_e32 v11, v11
	v_mul_f32_e32 v103, 0x4038aa3b, v164
	v_exp_f32_e32 v105, v103
	v_rcp_f32_e32 v103, v0
	v_add_f32_e32 v0, 1.0, v11
	v_rcp_f32_e32 v104, v0
	v_add_f32_e32 v0, 1.0, v105
	v_mul_f32_e32 v11, 0x4038aa3b, v165
	v_exp_f32_e32 v11, v11
	v_mul_f32_e32 v105, 0x4038aa3b, v166
	v_exp_f32_e32 v121, v105
	v_rcp_f32_e32 v105, v0
	v_add_f32_e32 v0, 1.0, v11
	v_rcp_f32_e32 v120, v0
	v_add_f32_e32 v0, 1.0, v121
	v_mul_f32_e32 v11, 0x4038aa3b, v167
	v_exp_f32_e32 v11, v11
	v_mul_f32_e32 v121, 0x4038aa3b, v168
	v_exp_f32_e32 v123, v121
	v_and_b32_e32 v153, 0xffff0000, v119
	v_and_b32_e32 v152, 0xffff0000, v118
	v_rcp_f32_e32 v121, v0
	v_add_f32_e32 v0, 1.0, v11
	v_lshlrev_b32_e32 v119, 16, v119
	v_lshlrev_b32_e32 v118, 16, v118
	v_rcp_f32_e32 v122, v0
	v_add_f32_e32 v0, 1.0, v123
	v_pk_mul_f32 v[118:119], v[160:161], v[118:119]
	v_lshlrev_b32_e32 v169, 16, v98
	v_rcp_f32_e32 v123, v0
	v_add_f32_e32 v0, v118, v119
	v_fma_f32 v0, v0, 0.5, -v169
	v_pk_mul_f32 v[118:119], v[160:161], v[152:153]
	v_and_b32_e32 v170, 0xffff0000, v98
	v_and_b32_e32 v155, 0xffff0000, v117
	v_and_b32_e32 v154, 0xffff0000, v116
	v_fmac_f32_e32 v169, v58, v0
	v_add_f32_e32 v0, v118, v119
	v_lshlrev_b32_e32 v117, 16, v117
	v_lshlrev_b32_e32 v116, 16, v116
	v_fma_f32 v0, v0, 0.5, -v170
	v_pk_mul_f32 v[116:117], v[160:161], v[116:117]
	v_lshlrev_b32_e32 v171, 16, v99
	v_fmac_f32_e32 v170, v59, v0
	v_add_f32_e32 v0, v116, v117
	v_fma_f32 v0, v0, 0.5, -v171
	v_pk_mul_f32 v[116:117], v[160:161], v[154:155]
	v_and_b32_e32 v172, 0xffff0000, v99
	v_and_b32_e32 v157, 0xffff0000, v115
	v_and_b32_e32 v156, 0xffff0000, v114
	v_fmac_f32_e32 v171, v60, v0
	v_add_f32_e32 v0, v116, v117
	v_lshlrev_b32_e32 v115, 16, v115
	v_lshlrev_b32_e32 v114, 16, v114
	v_fma_f32 v0, v0, 0.5, -v172
	v_pk_mul_f32 v[114:115], v[160:161], v[114:115]
	v_lshlrev_b32_e32 v173, 16, v100
	v_fmac_f32_e32 v172, v61, v0
	v_add_f32_e32 v0, v114, v115
	v_fma_f32 v0, v0, 0.5, -v173
	v_pk_mul_f32 v[114:115], v[160:161], v[156:157]
	v_and_b32_e32 v174, 0xffff0000, v100
	v_and_b32_e32 v159, 0xffff0000, v113
	v_and_b32_e32 v158, 0xffff0000, v112
	v_fmac_f32_e32 v173, v62, v0
	v_add_f32_e32 v0, v114, v115
	v_lshlrev_b32_e32 v113, 16, v113
	v_lshlrev_b32_e32 v112, 16, v112
	v_fma_f32 v0, v0, 0.5, -v174
	v_pk_mul_f32 v[112:113], v[160:161], v[112:113]
	v_lshlrev_b32_e32 v175, 16, v101
	v_fmac_f32_e32 v174, v63, v0
	v_add_f32_e32 v0, v112, v113
	v_fma_f32 v0, v0, 0.5, -v175
	v_pk_mul_f32 v[112:113], v[160:161], v[158:159]
	v_fmac_f32_e32 v175, v64, v0
	v_add_f32_e32 v0, v112, v113
	v_mul_f32_e32 v11, 0x4038aa3b, v169
	v_exp_f32_e32 v11, v11
	v_mul_f32_e32 v112, 0x4038aa3b, v170
	v_exp_f32_e32 v113, v112
	v_and_b32_e32 v176, 0xffff0000, v101
	v_fma_f32 v0, v0, 0.5, -v176
	v_fmac_f32_e32 v176, v65, v0
	v_add_f32_e32 v0, 1.0, v11
	v_rcp_f32_e32 v112, v0
	v_add_f32_e32 v0, 1.0, v113
	v_mul_f32_e32 v11, 0x4038aa3b, v171
	v_exp_f32_e32 v11, v11
	v_mul_f32_e32 v113, 0x4038aa3b, v172
	v_exp_f32_e32 v115, v113
	v_rcp_f32_e32 v113, v0
	v_add_f32_e32 v0, 1.0, v11
	v_rcp_f32_e32 v114, v0
	v_add_f32_e32 v0, 1.0, v115
	v_mul_f32_e32 v11, 0x4038aa3b, v173
	v_exp_f32_e32 v11, v11
	v_mul_f32_e32 v115, 0x4038aa3b, v174
	v_exp_f32_e32 v117, v115
	v_rcp_f32_e32 v115, v0
	v_add_f32_e32 v0, 1.0, v11
	v_rcp_f32_e32 v116, v0
	v_add_f32_e32 v0, 1.0, v117
	v_mul_f32_e32 v11, 0x4038aa3b, v175
	v_exp_f32_e32 v11, v11
	v_mul_f32_e32 v117, 0x4038aa3b, v176
	v_exp_f32_e32 v119, v117
	v_rcp_f32_e32 v117, v0
	v_add_f32_e32 v0, 1.0, v11
	v_rcp_f32_e32 v118, v0
	v_add_f32_e32 v0, 1.0, v119
	v_pk_fma_f32 v[102:103], v[102:103], 2.0, 1.0 op_sel_hi:[1,0,0] neg_lo:[1,0,0] neg_hi:[1,0,0]
	v_pk_fma_f32 v[104:105], v[104:105], 2.0, 1.0 op_sel_hi:[1,0,0] neg_lo:[1,0,0] neg_hi:[1,0,0]
	v_pk_fma_f32 v[120:121], v[120:121], 2.0, 1.0 op_sel_hi:[1,0,0] neg_lo:[1,0,0] neg_hi:[1,0,0]
	v_pk_fma_f32 v[122:123], v[122:123], 2.0, 1.0 op_sel_hi:[1,0,0] neg_lo:[1,0,0] neg_hi:[1,0,0]
	v_rcp_f32_e32 v119, v0
	v_cvt_pk_bf16_f32 v102, v102, v103
	v_cvt_pk_bf16_f32 v103, v104, v105
	v_cvt_pk_bf16_f32 v104, v120, v121
	v_cvt_pk_bf16_f32 v105, v122, v123
	v_pk_fma_f32 v[112:113], v[112:113], 2.0, 1.0 op_sel_hi:[1,0,0] neg_lo:[1,0,0] neg_hi:[1,0,0]
	v_pk_fma_f32 v[114:115], v[114:115], 2.0, 1.0 op_sel_hi:[1,0,0] neg_lo:[1,0,0] neg_hi:[1,0,0]
	v_pk_fma_f32 v[116:117], v[116:117], 2.0, 1.0 op_sel_hi:[1,0,0] neg_lo:[1,0,0] neg_hi:[1,0,0]
	v_pk_fma_f32 v[120:121], v[118:119], 2.0, 1.0 op_sel_hi:[1,0,0] neg_lo:[1,0,0] neg_hi:[1,0,0]
	v_cvt_pk_bf16_f32 v112, v112, v113
	v_cvt_pk_bf16_f32 v113, v114, v115
	v_cvt_pk_bf16_f32 v114, v116, v117
	v_cvt_pk_bf16_f32 v115, v120, v121
	v_mfma_f32_16x16x32_bf16 v[116:119], v[102:105], v[18:21], 0
	v_lshl_or_b32 v11, s19, 12, v143
	v_add_u32_e32 v11, v144, v11
	s_add_i32 s10, s19, 1
	v_mfma_f32_16x16x32_bf16 v[116:119], v[112:115], v[22:25], v[116:119]
	s_cmp_lg_u32 s19, 2
	s_cselect_b32 s19, s10, 0
	s_nop 5
	v_add_f32_e32 v0, v129, v116
	v_add_f32_e32 v116, v129, v117
	v_mul_f32_e32 v116, 0xbfb8aa3b, v116
	v_exp_f32_e32 v116, v116
	v_add_f32_e32 v117, v129, v118
	v_mul_f32_e32 v117, 0xbfb8aa3b, v117
	v_exp_f32_e32 v117, v117
	v_add_f32_e32 v116, 1.0, v116
	v_rcp_f32_e32 v116, v116
	v_mul_f32_e32 v0, 0xbfb8aa3b, v0
	v_exp_f32_e32 v0, v0
	v_mul_f32_e32 v116, 0xbf60028b, v116
	v_exp_f32_e32 v120, v116
	v_add_f32_e32 v116, 1.0, v117
	v_rcp_f32_e32 v116, v116
	v_add_f32_e32 v117, v129, v119
	v_mul_f32_e32 v117, 0xbfb8aa3b, v117
	v_exp_f32_e32 v121, v117
	v_mul_f32_e32 v122, 0xbf1b4598, v116
	v_mfma_f32_16x16x32_bf16 v[116:119], v[102:105], v[26:29], 0
	v_add_f32_e32 v0, 1.0, v0
	v_rcp_f32_e32 v0, v0
	v_add_f32_e32 v121, 1.0, v121
	v_mfma_f32_16x16x32_bf16 v[116:119], v[112:115], v[30:33], v[116:119]
	v_rcp_f32_e32 v121, v121
	v_mul_f32_e32 v0, 0xbf60028b, v0
	v_exp_f32_e32 v0, v0
	v_mul_f32_e32 v122, 0x3fb8aa3b, v122
	s_nop 2
	v_add_f32_e32 v116, v130, v116
	v_mul_f32_e32 v116, 0xbfb8aa3b, v116
	v_add_f32_e32 v117, v130, v117
	v_exp_f32_e32 v116, v116
	v_mul_f32_e32 v117, 0xbfb8aa3b, v117
	v_exp_f32_e32 v117, v117
	v_add_f32_e32 v118, v130, v118
	v_add_f32_e32 v116, 1.0, v116
	v_rcp_f32_e32 v116, v116
	v_add_f32_e32 v117, 1.0, v117
	v_rcp_f32_e32 v117, v117
	v_mul_f32_e32 v118, 0xbfb8aa3b, v118
	v_exp_f32_e32 v118, v118
	v_mul_f32_e32 v116, 0xbf60028b, v116
	v_exp_f32_e32 v116, v116
	v_mul_f32_e32 v117, 0xbf60028b, v117
	v_exp_f32_e32 v117, v117
	v_add_f32_e32 v118, 1.0, v118
	v_rcp_f32_e32 v118, v118
	ds_write2_b32 v11, v0, v116 offset1:16
	ds_write2_b32 v11, v120, v117 offset0:64 offset1:80
	v_add_f32_e32 v116, v130, v119
	v_mul_f32_e32 v116, 0xbfb8aa3b, v116
	v_mul_f32_e32 v0, 0xbf1b4598, v118
	v_exp_f32_e32 v120, v116
	v_mfma_f32_16x16x32_bf16 v[116:119], v[102:105], v[34:37], 0
	v_mul_f32_e32 v0, 0x3fb8aa3b, v0
	v_add_f32_e32 v120, 1.0, v120
	v_mfma_f32_16x16x32_bf16 v[116:119], v[112:115], v[38:41], v[116:119]
	v_rcp_f32_e32 v120, v120
	v_exp_f32_e32 v122, v122
	v_mul_f32_e32 v121, 0xbf60028b, v121
	v_mfma_f32_16x16x32_bf16 v[102:105], v[102:105], v[42:45], 0
	s_nop 2
	v_add_f32_e32 v116, v131, v116
	v_mul_f32_e32 v116, 0xbfb8aa3b, v116
	v_exp_f32_e32 v116, v116
	v_add_f32_e32 v117, v131, v117
	v_mfma_f32_16x16x32_bf16 v[102:105], v[112:115], v[46:49], v[102:105]
	v_mul_f32_e32 v117, 0xbfb8aa3b, v117
	v_add_f32_e32 v116, 1.0, v116
	v_exp_f32_e32 v0, v0
	v_mul_f32_e32 v120, 0xbf60028b, v120
	v_rcp_f32_e32 v116, v116
	v_exp_f32_e32 v117, v117
	v_exp_f32_e32 v121, v121
	v_exp_f32_e32 v120, v120
	v_add_f32_e32 v102, v132, v102
	v_mul_f32_e32 v102, 0xbfb8aa3b, v102
	v_add_f32_e32 v103, v132, v103
	ds_write2_b32 v11, v122, v0 offset0:128 offset1:144
	ds_write2_b32 v11, v121, v120 offset0:192 offset1:208
	v_mul_f32_e32 v0, 0xbf1b4598, v116
	v_add_f32_e32 v116, 1.0, v117
	v_add_f32_e32 v117, v131, v118
	v_exp_f32_e32 v102, v102
	v_mul_f32_e32 v103, 0xbfb8aa3b, v103
	v_add_f32_e32 v104, v132, v104
	v_mul_f32_e32 v117, 0xbfb8aa3b, v117
	v_add_f32_e32 v118, v131, v119
	v_exp_f32_e32 v103, v103
	v_mul_f32_e32 v104, 0xbfb8aa3b, v104
	v_add_f32_e32 v105, v132, v105
	v_exp_f32_e32 v117, v117
	v_mul_f32_e32 v118, 0xbfb8aa3b, v118
	v_exp_f32_e32 v104, v104
	v_mul_f32_e32 v105, 0xbfb8aa3b, v105
	v_exp_f32_e32 v118, v118
	v_exp_f32_e32 v105, v105
	v_add_f32_e32 v102, 1.0, v102
	v_rcp_f32_e32 v102, v102
	v_add_f32_e32 v103, 1.0, v103
	v_rcp_f32_e32 v116, v116
	v_add_f32_e32 v117, 1.0, v117
	v_rcp_f32_e32 v103, v103
	v_add_f32_e32 v104, 1.0, v104
	v_rcp_f32_e32 v117, v117
	v_add_f32_e32 v118, 1.0, v118
	v_rcp_f32_e32 v104, v104
	v_add_f32_e32 v105, 1.0, v105
	v_rcp_f32_e32 v118, v118
	v_rcp_f32_e32 v105, v105
	v_mul_f32_e32 v0, 0x3fb8aa3b, v0
	v_mul_f32_e32 v102, 0xbf60028b, v102
	v_exp_f32_e32 v0, v0
	v_mul_f32_e32 v116, 0xbf60028b, v116
	v_exp_f32_e32 v102, v102
	v_mul_f32_e32 v103, 0xbf60028b, v103
	v_exp_f32_e32 v116, v116
	v_mul_f32_e32 v117, 0xbf60028b, v117
	v_exp_f32_e32 v103, v103
	v_mul_f32_e32 v104, 0xbf60028b, v104
	v_exp_f32_e32 v117, v117
	v_mul_f32_e32 v118, 0xbf60028b, v118
	v_exp_f32_e32 v104, v104
	v_mul_f32_e32 v105, 0xbf60028b, v105
	v_exp_f32_e32 v112, v118
	v_exp_f32_e32 v105, v105
	ds_write2_b32 v11, v0, v102 offset0:32 offset1:48
	ds_write2_b32 v11, v116, v103 offset0:96 offset1:112
	ds_write2_b32 v11, v117, v104 offset0:160 offset1:176
	ds_write2_b32 v11, v112, v105 offset0:224 offset1:240
